# speedup vs baseline: 1.0101x; 1.0054x over previous
; __device__ __forceinline__ unsigned cvt_pk_bf16(float lo, float hi) { const f32x2 v = {lo, hi}; const bf16v2 r = __builtin_convertvector(v, bf16v2); return __builtin_bit_cast(unsigned, r); }
; __device__ __forceinline__ float bf_lo(unsigned u) { return __uint_as_float(u << 16); }
; __device__ __forceinline__ float bf_hi(unsigned u) { return __uint_as_float(u & 0xffff0000u); }
; __device__ __forceinline__ int otid() { int t = threadIdx.x; asm volatile("" : "+v"(t)); return t; }
; __device__ __forceinline__ int obid() { int b = blockIdx.x; asm volatile("" : "+s"(b)); return b; }
; __device__ void attn_combine(const bf16_t* AP, const float* LSE, bf16_t* MIX) {
;     ...
;     for (int i = obid() * 512 + otid(); i < n; i += gridDim.x * 512) {
;         const int tok = i >> 7, ch = i & 127, h = ch >> 4;
;         const float l0 = LSE[((size_t)0 * T + tok) * 8 + h], l1 = LSE[((size_t)1 * T + tok) * 8 + h], l2 = LSE[((size_t)2 * T + tok) * 8 + h];
;         const float m = fmaxf(l0, fmaxf(l1, l2)); float w0 = __expf(l0 - m), w1 = __expf(l1 - m), w2 = __expf(l2 - m); const float rs = 1.0f / (w0 + w1 + w2); w0 *= rs; w1 *= rs; w2 *= rs;
;         const u32x4 a = *(const u32x4*)(AP + ((size_t)0 * T + tok) * 1024 + ch * 8), b = *(const u32x4*)(AP + ((size_t)1 * T + tok) * 1024 + ch * 8), c = *(const u32x4*)(AP + ((size_t)2 * T + tok) * 1024 + ch * 8);
;         u32x4 w;
; #pragma unroll
;         for (int e = 0; e < 4; ++e) w[e] = cvt_pk_bf16(w0 * bf_lo(a[e]) + w1 * bf_lo(b[e]) + w2 * bf_lo(c[e]), w0 * bf_hi(a[e]) + w1 * bf_hi(b[e]) + w2 * bf_hi(c[e]));
;         *(u32x4*)(MIX + (size_t)tok * DM + ch * 8) = w;
.LBB0_297:
	v_ashrrev_i32_e32 v8, 7, v10
	v_ashrrev_i32_e32 v9, 31, v8
	v_lshlrev_b64 v[12:13], 5, v[8:9]
	s_mov_b64 s[4:5], 0x6000
	v_lshl_add_u64 v[12:13], v[2:3], 0, v[12:13]
	v_lshl_add_u64 v[16:17], v[8:9], 0, s[4:5]
	global_load_dword v0, v[12:13], off
	v_lshlrev_b64 v[12:13], 5, v[16:17]
	v_lshl_add_u64 v[12:13], v[2:3], 0, v[12:13]
	v_lshl_add_u64 v[20:21], v[8:9], 0, s[6:7]
	global_load_dword v11, v[12:13], off
	v_lshlrev_b64 v[12:13], 5, v[20:21]
	v_lshl_add_u64 v[12:13], v[2:3], 0, v[12:13]
	global_load_dword v12, v[12:13], off
	v_lshlrev_b64 v[20:21], 11, v[20:21]
	v_lshl_add_u64 v[20:21], v[4:5], 0, v[20:21]
	global_load_dwordx4 v[20:23], v[20:21], off nt
	v_lshlrev_b64 v[16:17], 11, v[16:17]
	v_lshl_add_u64 v[16:17], v[4:5], 0, v[16:17]
	v_lshlrev_b64 v[34:35], 11, v[8:9]
	v_lshl_add_u64 v[34:35], v[4:5], 0, v[34:35]
	global_load_dwordx4 v[36:39], v[34:35], off nt
	global_load_dwordx4 v[40:43], v[16:17], off nt
	v_add_u32_e32 v54, s67, v10
	v_cmp_gt_i32_e32 vcc, 0x300000, v54
	s_nop 1
	s_and_saveexec_b64 s[12:13], vcc
	v_ashrrev_i32_e32 v58, 7, v54
	v_ashrrev_i32_e32 v59, 31, v58
	v_lshlrev_b64 v[62:63], 5, v[58:59]
	s_mov_b64 s[4:5], 0x6000
	v_lshl_add_u64 v[62:63], v[2:3], 0, v[62:63]
	v_lshl_add_u64 v[66:67], v[58:59], 0, s[4:5]
	global_load_dword v50, v[62:63], off
	v_lshlrev_b64 v[62:63], 5, v[66:67]
	v_lshl_add_u64 v[62:63], v[2:3], 0, v[62:63]
	v_lshl_add_u64 v[70:71], v[58:59], 0, s[6:7]
	global_load_dword v61, v[62:63], off
	v_lshlrev_b64 v[62:63], 5, v[70:71]
	v_lshl_add_u64 v[62:63], v[2:3], 0, v[62:63]
	global_load_dword v62, v[62:63], off
	v_lshlrev_b64 v[70:71], 11, v[70:71]
	v_lshl_add_u64 v[70:71], v[4:5], 0, v[70:71]
	global_load_dwordx4 v[70:73], v[70:71], off nt
	v_lshlrev_b64 v[66:67], 11, v[66:67]
	v_lshl_add_u64 v[66:67], v[4:5], 0, v[66:67]
	v_lshlrev_b64 v[84:85], 11, v[58:59]
	v_lshl_add_u64 v[84:85], v[4:5], 0, v[84:85]
	global_load_dwordx4 v[86:89], v[84:85], off nt
	global_load_dwordx4 v[90:93], v[66:67], off nt
	s_mov_b64 exec, s[12:13]
	v_add_u32_e32 v10, s67, v54
	s_waitcnt vmcnt(9)
	v_max3_f32 v13, v0, v11, v12
	v_sub_f32_e32 v0, v0, v13
	v_mul_f32_e32 v0, 0x3fb8aa3b, v0
	v_exp_f32_e32 v25, v0
	v_sub_f32_e32 v0, v11, v13
	v_mul_f32_e32 v0, 0x3fb8aa3b, v0
	v_exp_f32_e32 v24, v0
	v_sub_f32_e32 v0, v12, v13
	v_mul_f32_e32 v0, 0x3fb8aa3b, v0
	v_exp_f32_e32 v11, v0
	v_add_f32_e32 v0, v25, v24
	s_waitcnt vmcnt(8)
	v_lshlrev_b32_e32 v32, 16, v20
	v_and_b32_e32 v33, 0xffff0000, v20
	v_add_f32_e32 v0, v11, v0
	v_div_scale_f32 v12, s[4:5], v0, v0, 1.0
	v_rcp_f32_e32 v13, v12
	v_lshlrev_b32_e32 v20, 16, v21
	v_and_b32_e32 v21, 0xffff0000, v21
	v_fma_f32 v14, -v12, v13, 1.0
	v_fmac_f32_e32 v13, v14, v13
	v_div_scale_f32 v14, vcc, 1.0, v0, 1.0
	v_mul_f32_e32 v15, v14, v13
	v_fma_f32 v18, -v12, v15, v14
	v_fmac_f32_e32 v15, v18, v13
	v_fma_f32 v12, -v12, v15, v14
	v_div_fmas_f32 v12, v12, v13, v15
	v_div_fixup_f32 v0, v12, v0, 1.0
	v_pk_mul_f32 v[24:25], v[24:25], v[0:1] op_sel_hi:[1,0]
	v_mul_f32_e32 v26, v11, v0
	v_lshlrev_b64 v[8:9], 12, v[8:9]
	v_lshl_add_u64 v[8:9], v[6:7], 0, v[8:9]
	s_waitcnt vmcnt(6)
	v_lshlrev_b32_e32 v30, 16, v36
	v_and_b32_e32 v29, 0xffff0000, v36
	s_waitcnt vmcnt(6)
; __device__ __forceinline__ unsigned cvt_pk_bf16(float lo, float hi) { const f32x2 v = {lo, hi}; const bf16v2 r = __builtin_convertvector(v, bf16v2); return __builtin_bit_cast(unsigned, r); }
; __device__ __forceinline__ float bf_lo(unsigned u) { return __uint_as_float(u << 16); }
; __device__ __forceinline__ float bf_hi(unsigned u) { return __uint_as_float(u & 0xffff0000u); }
; __device__ __forceinline__ int otid() { int t = threadIdx.x; asm volatile("" : "+v"(t)); return t; }
; __device__ __forceinline__ int obid() { int b = blockIdx.x; asm volatile("" : "+s"(b)); return b; }
; __device__ void attn_combine(const bf16_t* AP, const float* LSE, bf16_t* MIX) {
;     ...
;     for (int i = obid() * 512 + otid(); i < n; i += gridDim.x * 512) {
;         const int tok = i >> 7, ch = i & 127, h = ch >> 4;
;         const float l0 = LSE[((size_t)0 * T + tok) * 8 + h], l1 = LSE[((size_t)1 * T + tok) * 8 + h], l2 = LSE[((size_t)2 * T + tok) * 8 + h];
;         const float m = fmaxf(l0, fmaxf(l1, l2)); float w0 = __expf(l0 - m), w1 = __expf(l1 - m), w2 = __expf(l2 - m); const float rs = 1.0f / (w0 + w1 + w2); w0 *= rs; w1 *= rs; w2 *= rs;
;         const u32x4 a = *(const u32x4*)(AP + ((size_t)0 * T + tok) * 1024 + ch * 8), b = *(const u32x4*)(AP + ((size_t)1 * T + tok) * 1024 + ch * 8), c = *(const u32x4*)(AP + ((size_t)2 * T + tok) * 1024 + ch * 8);
;         u32x4 w;
; #pragma unroll
;         for (int e = 0; e < 4; ++e) w[e] = cvt_pk_bf16(w0 * bf_lo(a[e]) + w1 * bf_lo(b[e]) + w2 * bf_lo(c[e]), w0 * bf_hi(a[e]) + w1 * bf_hi(b[e]) + w2 * bf_hi(c[e]));
;         *(u32x4*)(MIX + (size_t)tok * DM + ch * 8) = w;
	v_and_b32_e32 v31, 0xffff0000, v40
	v_lshlrev_b32_e32 v28, 16, v40
	v_pk_mul_f32 v[30:31], v[24:25], v[30:31] op_sel:[1,0] op_sel_hi:[0,1]
	v_pk_fma_f32 v[28:29], v[24:25], v[28:29], v[30:31]
	v_lshlrev_b32_e32 v40, 16, v37
	v_pk_fma_f32 v[28:29], v[26:27], v[32:33], v[28:29] op_sel_hi:[0,1,1]
	v_cvt_pk_bf16_f32 v36, v28, v29
	v_lshlrev_b32_e32 v28, 16, v41
	v_and_b32_e32 v41, 0xffff0000, v41
	v_and_b32_e32 v29, 0xffff0000, v37
	v_pk_mul_f32 v[40:41], v[24:25], v[40:41] op_sel:[1,0] op_sel_hi:[0,1]
	v_pk_fma_f32 v[40:41], v[24:25], v[28:29], v[40:41]
	v_lshlrev_b32_e32 v28, 16, v22
	v_pk_fma_f32 v[40:41], v[26:27], v[20:21], v[40:41] op_sel_hi:[0,1,1]
	v_lshlrev_b32_e32 v20, 16, v38
	v_and_b32_e32 v21, 0xffff0000, v42
	v_cvt_pk_bf16_f32 v37, v40, v41
	v_lshlrev_b32_e32 v40, 16, v42
	v_and_b32_e32 v41, 0xffff0000, v38
	v_pk_mul_f32 v[20:21], v[24:25], v[20:21] op_sel:[1,0] op_sel_hi:[0,1]
	v_and_b32_e32 v29, 0xffff0000, v22
	v_pk_fma_f32 v[40:41], v[24:25], v[40:41], v[20:21]
	v_lshlrev_b32_e32 v42, 16, v39
	v_pk_fma_f32 v[40:41], v[26:27], v[28:29], v[40:41] op_sel_hi:[0,1,1]
	v_cvt_pk_bf16_f32 v38, v40, v41
	v_lshlrev_b32_e32 v40, 16, v43
	v_and_b32_e32 v43, 0xffff0000, v43
	v_and_b32_e32 v41, 0xffff0000, v39
	v_pk_mul_f32 v[42:43], v[24:25], v[42:43] op_sel:[1,0] op_sel_hi:[0,1]
	v_pk_fma_f32 v[40:41], v[24:25], v[40:41], v[42:43]
	v_lshlrev_b32_e32 v42, 16, v23
	v_and_b32_e32 v43, 0xffff0000, v23
	v_pk_fma_f32 v[40:41], v[26:27], v[42:43], v[40:41] op_sel_hi:[0,1,1]
	v_cvt_pk_bf16_f32 v39, v40, v41
	global_store_dwordx4 v[8:9], v[36:39], off
	s_waitcnt vmcnt(4)
	v_max3_f32 v63, v50, v61, v62
	v_sub_f32_e32 v50, v50, v63
	v_mul_f32_e32 v50, 0x3fb8aa3b, v50
	v_exp_f32_e32 v75, v50
	v_sub_f32_e32 v50, v61, v63
	v_mul_f32_e32 v50, 0x3fb8aa3b, v50
	v_exp_f32_e32 v74, v50
	v_sub_f32_e32 v50, v62, v63
	v_mul_f32_e32 v50, 0x3fb8aa3b, v50
	v_exp_f32_e32 v61, v50
	v_add_f32_e32 v50, v75, v74
	s_waitcnt vmcnt(3)
	v_lshlrev_b32_e32 v82, 16, v70
	v_and_b32_e32 v83, 0xffff0000, v70
	v_add_f32_e32 v50, v61, v50
	v_div_scale_f32 v62, s[4:5], v50, v50, 1.0
	v_rcp_f32_e32 v63, v62
	v_lshlrev_b32_e32 v70, 16, v71
	v_and_b32_e32 v71, 0xffff0000, v71
	v_fma_f32 v64, -v62, v63, 1.0
	v_fmac_f32_e32 v63, v64, v63
	v_div_scale_f32 v64, vcc, 1.0, v50, 1.0
	v_mul_f32_e32 v65, v64, v63
	v_fma_f32 v68, -v62, v65, v64
	v_fmac_f32_e32 v65, v68, v63
	v_fma_f32 v62, -v62, v65, v64
	v_div_fmas_f32 v62, v62, v63, v65
	v_div_fixup_f32 v50, v62, v50, 1.0
	v_pk_mul_f32 v[74:75], v[74:75], v[50:51] op_sel_hi:[1,0]
	v_mul_f32_e32 v76, v61, v50
	v_lshlrev_b64 v[58:59], 12, v[58:59]
	v_lshl_add_u64 v[58:59], v[6:7], 0, v[58:59]
	s_waitcnt vmcnt(1)
	v_lshlrev_b32_e32 v80, 16, v86
	v_and_b32_e32 v79, 0xffff0000, v86
	s_waitcnt vmcnt(1)
	v_and_b32_e32 v81, 0xffff0000, v90
	v_lshlrev_b32_e32 v78, 16, v90
	v_pk_mul_f32 v[80:81], v[74:75], v[80:81] op_sel:[1,0] op_sel_hi:[0,1]
	v_pk_fma_f32 v[78:79], v[74:75], v[78:79], v[80:81]
	v_lshlrev_b32_e32 v90, 16, v87
	v_pk_fma_f32 v[78:79], v[76:77], v[82:83], v[78:79] op_sel_hi:[0,1,1]
	v_cvt_pk_bf16_f32 v86, v78, v79
	v_lshlrev_b32_e32 v78, 16, v91
	v_and_b32_e32 v91, 0xffff0000, v91
	v_and_b32_e32 v79, 0xffff0000, v87
	v_pk_mul_f32 v[90:91], v[74:75], v[90:91] op_sel:[1,0] op_sel_hi:[0,1]
	v_pk_fma_f32 v[90:91], v[74:75], v[78:79], v[90:91]
	v_lshlrev_b32_e32 v78, 16, v72
	v_pk_fma_f32 v[90:91], v[76:77], v[70:71], v[90:91] op_sel_hi:[0,1,1]
	v_lshlrev_b32_e32 v70, 16, v88
	v_and_b32_e32 v71, 0xffff0000, v92
	v_cvt_pk_bf16_f32 v87, v90, v91
	v_lshlrev_b32_e32 v90, 16, v92
	v_and_b32_e32 v91, 0xffff0000, v88
	v_pk_mul_f32 v[70:71], v[74:75], v[70:71] op_sel:[1,0] op_sel_hi:[0,1]
	v_and_b32_e32 v79, 0xffff0000, v72
	v_pk_fma_f32 v[90:91], v[74:75], v[90:91], v[70:71]
	v_lshlrev_b32_e32 v92, 16, v89
	v_pk_fma_f32 v[90:91], v[76:77], v[78:79], v[90:91] op_sel_hi:[0,1,1]
	v_cvt_pk_bf16_f32 v88, v90, v91
	v_lshlrev_b32_e32 v90, 16, v93
	v_and_b32_e32 v93, 0xffff0000, v93
	v_and_b32_e32 v91, 0xffff0000, v89
	v_pk_mul_f32 v[92:93], v[74:75], v[92:93] op_sel:[1,0] op_sel_hi:[0,1]
	v_pk_fma_f32 v[90:91], v[74:75], v[90:91], v[92:93]
	v_lshlrev_b32_e32 v92, 16, v73
	v_and_b32_e32 v93, 0xffff0000, v73
	v_pk_fma_f32 v[90:91], v[76:77], v[92:93], v[90:91] op_sel_hi:[0,1,1]
	v_cvt_pk_bf16_f32 v89, v90, v91
	v_cmp_gt_i32_e32 vcc, 0x300000, v54
	s_nop 1
	s_and_saveexec_b64 s[12:13], vcc
	global_store_dwordx4 v[58:59], v[86:89], off
	s_mov_b64 exec, s[12:13]
	s_mov_b32 s4, 0x2fffff
	v_cmp_lt_i32_e32 vcc, s4, v10
	s_nop 1
	s_or_b64 s[2:3], vcc, s[2:3]
	s_andn2_b64 exec, exec, s[2:3]
	s_cbranch_execnz .LBB0_297
